# SSD chunk loop x-conv: pk_mul+add+add -> two v_fma_f32 per tap pair (same order), copies forwarded, dead movs dropped
# baseline (speedup 1.0000x reference)
; __device__ __forceinline__ float ex2(float x) { return __builtin_amdgcn_exp2f(x); }
; __device__ __forceinline__ float silu_f(float x) { return x * sigm(x); }
; #define LAS __attribute__((address_space(3)))
; __device__ __forceinline__ void ssd_stream(const Frame& F, const Args& A, int sidx) {
;     ...
;             for (int i = 0; i < 2; ++i) { *(LAS v4u*)(XST + xdst + 64 * i * XS_) = pfx[i]; if (lane < 24) *(LAS v4u*)(HAL + (3 * i + (lane >> 3)) * XS_ + 16 * (lane & 7)) = pfh[i]; }
;             v4u rw[2][4];
; #pragma unroll
;             for (int i = 0; i < 2; ++i)
; #pragma unroll
;                 for (int k = 0; k < 4; ++k) { const int lr = (lane >> 3) + k - 3;
;                     LAS unsigned char* src = lr >= 0 ? XST + (8 * w + lr + 64 * i) * XS_ + 16 * (lane & 7) : HAL + (3 * i + 3 + lr) * XS_ + 16 * (lane & 7);
;                     rw[i][k] = *(LAS v4u*)src; }
;             f32x4 cwa[5], cwb[5];
; #pragma unroll
;             for (int k = 0; k < 5; ++k) { cwa[k] = *(LAS f32x4*)(CWL + 64 * k + 8 * (lane & 7)); cwb[k] = *(LAS f32x4*)(CWL + 64 * k + 8 * (lane & 7) + 4); }
;             asm volatile("s_waitcnt lgkmcnt(0)" ::: "memory");
; #pragma unroll
;             for (int i = 0; i < 2; ++i) {
;                 const int row = (tid >> 3) + 64 * i;
;                 float y[8];
; #pragma unroll
;                 for (int e = 0; e < 8; ++e) y[e] = e < 4 ? cwa[4][e] : cwb[4][e - 4];
; #pragma unroll
;                 for (int k = 0; k < 4; ++k) { const v4u r = rw[i][k];
;                     y[0] += cwa[k][0] * bflo(r.x); y[1] += cwa[k][1] * bfhi(r.x); y[2] += cwa[k][2] * bflo(r.y); y[3] += cwa[k][3] * bfhi(r.y);
;                     y[4] += cwb[k][0] * bflo(r.z); y[5] += cwb[k][1] * bfhi(r.z); y[6] += cwb[k][2] * bflo(r.w); y[7] += cwb[k][3] * bfhi(r.w); }
; #pragma unroll
;                 for (int e = 0; e < 8; ++e) y[e] = silu_f(y[e]);
;                 *(LAS bf16x8*)(XT + xdst + 64 * i * XS_) = packf8(y[0], y[1], y[2], y[3], y[4], y[5], y[6], y[7]);
;                 const float te = ex2(aL - arr[row]) * arr[128 + row];
;                 *(LAS bf16x8*)(XST + xdst + 64 * i * XS_) = packf8(y[0] * te, y[1] * te, y[2] * te, y[3] * te, y[4] * te, y[5] * te, y[6] * te, y[7] * te);
.LBB0_1297:
	s_or_b64 exec, exec, s[26:27]
	ds_read_b128 v[108:111], v212
	ds_read_b128 v[112:115], v213
	ds_read_b128 v[116:119], v214
	ds_read_b128 v[120:123], v215
	ds_read_b128 v[34:37], v216
	ds_read_b128 v[38:41], v217
	ds_read_b128 v[22:25], v218
	ds_read_b128 v[26:29], v219
	ds_read_b128 v[98:101], v207
	ds_read_b128 v[42:45], v207 offset:16
	ds_read_b128 v[124:127], v207 offset:256
	ds_read_b128 v[128:131], v207 offset:272
	ds_read_b128 v[30:33], v207 offset:512
	ds_read_b128 v[18:21], v207 offset:528
	ds_read_b128 v[132:135], v207 offset:768
	ds_read_b128 v[178:181], v207 offset:784
	ds_read_b128 v[102:105], v207 offset:1024
	ds_read_b128 v[46:49], v207 offset:1040
	s_waitcnt lgkmcnt(14)
	v_lshlrev_b32_e32 v137, 16, v108
	v_lshlrev_b32_e32 v136, 16, v112
	s_waitcnt lgkmcnt(7)
	v_mov_b32_e32 v182, v124
	v_mov_b32_e32 v183, v98
	s_waitcnt lgkmcnt(0)
	v_lshl_add_u32 v107, v175, 2, s78
	s_waitcnt lgkmcnt(1)
	v_fma_f32 v98, v98, v137, v102
	v_fma_f32 v140, v124, v136, v98
	v_and_b32_e32 v137, 0xffff0000, v108
	v_and_b32_e32 v136, 0xffff0000, v112
	v_mov_b32_e32 v98, v125
	v_fma_f32 v108, v99, v137, v103
	v_fma_f32 v184, v125, v136, v108
	v_lshlrev_b32_e32 v125, 16, v109
	v_lshlrev_b32_e32 v124, 16, v113
	v_mov_b32_e32 v137, v100
	v_and_b32_e32 v109, 0xffff0000, v109
	v_fma_f32 v100, v100, v125, v104
	v_fma_f32 v185, v126, v124, v100
	v_and_b32_e32 v108, 0xffff0000, v113
	v_mov_b32_e32 v100, v127
	v_mov_b32_e32 v112, v128
	v_fma_f32 v109, v101, v109, v105
	v_fma_f32 v186, v127, v108, v109
	v_lshlrev_b32_e32 v109, 16, v110
	v_lshlrev_b32_e32 v108, 16, v114
	v_mov_b32_e32 v113, v42
	v_mov_b32_e32 v124, v130
	s_waitcnt lgkmcnt(0)
	v_fma_f32 v42, v42, v109, v46
	v_fma_f32 v128, v128, v108, v42
	v_and_b32_e32 v109, 0xffff0000, v110
	v_and_b32_e32 v108, 0xffff0000, v114
	v_mov_b32_e32 v42, v129
	v_mov_b32_e32 v125, v44
	v_fma_f32 v109, v43, v109, v47
	v_fma_f32 v110, v129, v108, v109
	v_lshlrev_b32_e32 v109, 16, v111
	v_lshlrev_b32_e32 v108, 16, v115
	v_mov_b32_e32 v114, v132
	v_fma_f32 v44, v44, v109, v48
	v_fma_f32 v129, v130, v108, v44
	v_and_b32_e32 v109, 0xffff0000, v111
	v_and_b32_e32 v108, 0xffff0000, v115
	v_mov_b32_e32 v44, v131
	v_mov_b32_e32 v115, v30
	v_fma_f32 v109, v45, v109, v49
	v_fma_f32 v111, v131, v108, v109
	v_lshlrev_b32_e32 v109, 16, v116
	v_lshlrev_b32_e32 v108, 16, v120
	v_fma_f32 v30, v30, v109, v140
	v_fma_f32 v130, v132, v108, v30
	v_and_b32_e32 v109, 0xffff0000, v116
	v_and_b32_e32 v108, 0xffff0000, v120
	v_mov_b32_e32 v30, v133
	v_mov_b32_e32 v127, v32
	v_fma_f32 v109, v31, v109, v184
	v_fma_f32 v131, v133, v108, v109
	v_lshlrev_b32_e32 v109, 16, v117
	v_lshlrev_b32_e32 v108, 16, v121
	v_fma_f32 v32, v32, v109, v185
	v_fma_f32 v132, v134, v108, v32
	v_and_b32_e32 v109, 0xffff0000, v117
	v_and_b32_e32 v108, 0xffff0000, v121
	v_mov_b32_e32 v117, v18
	v_fma_f32 v109, v33, v109, v186
	v_fma_f32 v133, v135, v108, v109
	v_lshlrev_b32_e32 v109, 16, v118
	v_lshlrev_b32_e32 v108, 16, v122
	v_fma_f32 v18, v18, v109, v128
	v_fma_f32 v128, v178, v108, v18
	v_and_b32_e32 v109, 0xffff0000, v118
	v_and_b32_e32 v108, 0xffff0000, v122
	v_mov_b32_e32 v121, v20
	v_fma_f32 v109, v19, v109, v110
	v_fma_f32 v110, v179, v108, v109
	v_lshlrev_b32_e32 v109, 16, v119
	v_lshlrev_b32_e32 v108, 16, v123
	v_mul_f32_e32 v122, 0xbfb8aa3b, v133
	v_fma_f32 v20, v20, v109, v129
	v_fma_f32 v118, v180, v108, v20
	v_and_b32_e32 v109, 0xffff0000, v119
	v_and_b32_e32 v108, 0xffff0000, v123
	v_mov_b32_e32 v20, v181
	v_mul_f32_e32 v119, 0xbfb8aa3b, v130
	v_fma_f32 v109, v21, v109, v111
	v_mul_f32_e32 v111, 0xbfb8aa3b, v131
	v_exp_f32_e32 v119, v119
	v_exp_f32_e32 v111, v111
	v_fma_f32 v108, v181, v108, v109
	v_exp_f32_e32 v122, v122
	v_add_f32_e32 v109, 1.0, v119
	v_add_f32_e32 v111, 1.0, v111
	v_rcp_f32_e32 v109, v109
	v_rcp_f32_e32 v111, v111
	v_mul_f32_e32 v119, 0xbfb8aa3b, v132
	v_exp_f32_e32 v119, v119
	v_mul_f32_e32 v123, v130, v109
	v_mul_f32_e32 v129, v131, v111
	v_add_f32_e32 v109, 1.0, v122
	v_mul_f32_e32 v111, 0xbfb8aa3b, v128
	v_mul_f32_e32 v122, 0xbfb8aa3b, v110
	v_rcp_f32_e32 v109, v109
	v_exp_f32_e32 v111, v111
	v_exp_f32_e32 v122, v122
	v_mul_f32_e32 v131, 0xbfb8aa3b, v108
	v_mul_f32_e32 v130, v133, v109
	v_add_f32_e32 v109, 1.0, v111
	v_add_f32_e32 v111, 1.0, v122
	v_mul_f32_e32 v122, 0xbfb8aa3b, v118
	v_exp_f32_e32 v122, v122
	v_exp_f32_e32 v131, v131
	v_add_f32_e32 v119, 1.0, v119
	v_rcp_f32_e32 v119, v119
	v_add_f32_e32 v122, 1.0, v122
	v_add_f32_e32 v131, 1.0, v131
	v_rcp_f32_e32 v109, v109
	v_rcp_f32_e32 v111, v111
	v_rcp_f32_e32 v122, v122
	v_rcp_f32_e32 v131, v131
	v_mul_f32_e32 v119, v132, v119
	v_mul_f32_e32 v128, v128, v109
	v_mul_f32_e32 v132, v110, v111
	v_mul_f32_e32 v118, v118, v122
	v_mul_f32_e32 v122, v108, v131
	v_cvt_pk_bf16_f32 v108, v123, v129
	v_cvt_pk_bf16_f32 v109, v119, v130
	v_cvt_pk_bf16_f32 v110, v128, v132
	v_cvt_pk_bf16_f32 v111, v118, v122
	ds_write_b128 v229, v[108:111]
	ds_read2st64_b32 v[108:109], v107 offset1:2
	s_lshl_b32 s92, s5, 7
	s_lshl_b64 s[64:65], s[92:93], 12
	s_cmp_lg_u32 s5, 63
	s_cselect_b64 s[60:61], -1, 0
	s_waitcnt lgkmcnt(0)
; __device__ __forceinline__ float ex2(float x) { return __builtin_amdgcn_exp2f(x); }
; __device__ __forceinline__ void ssd_stream(const Frame& F, const Args& A, int sidx) {
;     ...
;             for (int i = 0; i < 2; ++i) {
;                 const int row = (tid >> 3) + 64 * i;
;                 float y[8];
; #pragma unroll
;                 for (int e = 0; e < 8; ++e) y[e] = e < 4 ? cwa[4][e] : cwb[4][e - 4];
; #pragma unroll
;                 for (int k = 0; k < 4; ++k) { const v4u r = rw[i][k];
;                     y[0] += cwa[k][0] * bflo(r.x); y[1] += cwa[k][1] * bfhi(r.x); y[2] += cwa[k][2] * bflo(r.y); y[3] += cwa[k][3] * bfhi(r.y);
;                     y[4] += cwb[k][0] * bflo(r.z); y[5] += cwb[k][1] * bfhi(r.z); y[6] += cwb[k][2] * bflo(r.w); y[7] += cwb[k][3] * bfhi(r.w); }
; #pragma unroll
;                 for (int e = 0; e < 8; ++e) y[e] = silu_f(y[e]);
;                 *(LAS bf16x8*)(XT + xdst + 64 * i * XS_) = packf8(y[0], y[1], y[2], y[3], y[4], y[5], y[6], y[7]);
;                 const float te = ex2(aL - arr[row]) * arr[128 + row];
;                 *(LAS bf16x8*)(XST + xdst + 64 * i * XS_) = packf8(y[0] * te, y[1] * te, y[2] * te, y[3] * te, y[4] * te, y[5] * te, y[6] * te, y[7] * te);
;             }
; #pragma unroll
;             for (int i = 0; i < 4; ++i) { *(LAS v4u*)(BT + bdst + 32 * i * BS_) = pfb[i]; *(LAS v4u*)(CT + bdst + 32 * i * BS_) = pfc[i]; }
;         }
;         v2u zw[4];
;         { const GAS unsigned char* zb = Zg + (size_t)t0 * 4096;
; #pragma unroll
;           for (int q4 = 0; q4 < 4; ++q4) zw[q4] = *(const GAS v2u*)(zb + 16 * q4 + zoff); }
;         if (ck < 63) {
;             const GAS unsigned char* xb = XCg + (size_t)(t0 + 128) * 6144; const GAS unsigned char* rb = XBg + (size_t)(t0 + 128) * 6144;
; #pragma unroll
;             for (int i = 0; i < 2; ++i) { pfx[i] = *(const GAS v4u*)(rb + (size_t)i * (64 * 6144) + xoff);
;                 if (lane < 24) pfh[i] = *(const GAS v4u*)(rb + (ptrdiff_t)(hrow + 64 * i) * 6144 + hoff); }
; #pragma unroll
;             for (int i = 0; i < 4; ++i) { pfb[i] = *(const GAS v4u*)(xb + (size_t)i * (32 * 6144) + boff); pfc[i] = *(const GAS v4u*)(xb + (size_t)i * (32 * 6144) + 1024 + boff); }
;             if (w == 0) { const GAS unsigned char* db = DTg + (size_t)(t0 + 128) * 128; pd0 = *(const GAS float*)(db + doff); pd1 = *(const GAS float*)(db + 128 + doff); }
	v_sub_f32_e32 v108, v106, v108
	v_exp_f32_e32 v108, v108
	s_cmp_eq_u32 s5, 63
	v_mul_f32_e32 v108, v109, v108
	v_mul_f32_e32 v109, v123, v108
	v_mul_f32_e32 v110, v129, v108
	v_mul_f32_e32 v111, v119, v108
	v_mul_f32_e32 v119, v130, v108
	v_mul_f32_e32 v123, v128, v108
	v_mul_f32_e32 v128, v132, v108
	v_mul_f32_e32 v118, v118, v108
	v_mul_f32_e32 v122, v122, v108
	v_cvt_pk_bf16_f32 v108, v109, v110
	v_cvt_pk_bf16_f32 v109, v111, v119
	v_cvt_pk_bf16_f32 v110, v123, v128
	v_cvt_pk_bf16_f32 v111, v118, v122
	ds_write_b128 v229, v[108:111] offset:18432
	v_lshlrev_b32_e32 v109, 16, v34
	v_lshlrev_b32_e32 v108, 16, v38
	v_fma_f32 v102, v183, v109, v102
	v_fma_f32 v102, v182, v108, v102
	v_and_b32_e32 v109, 0xffff0000, v34
	v_and_b32_e32 v108, 0xffff0000, v38
	v_fma_f32 v34, v99, v109, v103
	v_fma_f32 v38, v98, v108, v34
	v_lshlrev_b32_e32 v99, 16, v35
	v_lshlrev_b32_e32 v98, 16, v39
	v_and_b32_e32 v35, 0xffff0000, v35
	v_fma_f32 v34, v137, v99, v104
	v_fma_f32 v98, v126, v98, v34
	v_and_b32_e32 v34, 0xffff0000, v39
	v_fma_f32 v35, v101, v35, v105
	v_fma_f32 v39, v100, v34, v35
	v_lshlrev_b32_e32 v35, 16, v36
	v_lshlrev_b32_e32 v34, 16, v40
	v_fma_f32 v35, v113, v35, v46
	v_fma_f32 v46, v112, v34, v35
	v_and_b32_e32 v35, 0xffff0000, v36
	v_and_b32_e32 v34, 0xffff0000, v40
	v_fma_f32 v35, v43, v35, v47
	v_fma_f32 v36, v42, v34, v35
	v_lshlrev_b32_e32 v35, 16, v37
	v_lshlrev_b32_e32 v34, 16, v41
	v_fma_f32 v35, v125, v35, v48
	v_fma_f32 v40, v124, v34, v35
	v_and_b32_e32 v35, 0xffff0000, v37
	v_and_b32_e32 v34, 0xffff0000, v41
	v_fma_f32 v35, v45, v35, v49
	v_fma_f32 v37, v44, v34, v35
	v_lshlrev_b32_e32 v35, 16, v22
	v_lshlrev_b32_e32 v34, 16, v26
	v_fma_f32 v35, v115, v35, v102
	v_fma_f32 v41, v114, v34, v35
	v_and_b32_e32 v35, 0xffff0000, v22
	v_and_b32_e32 v34, 0xffff0000, v26
	v_fma_f32 v22, v31, v35, v38
	v_fma_f32 v26, v30, v34, v22
	v_lshlrev_b32_e32 v31, 16, v23
	v_lshlrev_b32_e32 v30, 16, v27
	v_and_b32_e32 v23, 0xffff0000, v23
	v_fma_f32 v22, v127, v31, v98
	v_fma_f32 v30, v134, v30, v22
	v_and_b32_e32 v22, 0xffff0000, v27
	v_fma_f32 v23, v33, v23, v39
	v_fma_f32 v27, v135, v22, v23
	v_lshlrev_b32_e32 v23, 16, v24
	v_lshlrev_b32_e32 v22, 16, v28
	v_fma_f32 v23, v117, v23, v46
	v_fma_f32 v31, v178, v22, v23
	v_and_b32_e32 v23, 0xffff0000, v24
	v_and_b32_e32 v22, 0xffff0000, v28
	v_mul_f32_e32 v24, 0xbfb8aa3b, v41
	v_fma_f32 v19, v19, v23, v36
	v_fma_f32 v22, v179, v22, v19
	v_lshlrev_b32_e32 v19, 16, v25
	v_lshlrev_b32_e32 v18, 16, v29
	v_exp_f32_e32 v24, v24
	v_fma_f32 v19, v121, v19, v40
	v_fma_f32 v23, v180, v18, v19
	v_and_b32_e32 v19, 0xffff0000, v25
	v_and_b32_e32 v18, 0xffff0000, v29
	v_pk_mul_f32 v[18:19], v[20:21], v[18:19]
	v_mul_f32_e32 v20, 0xbfb8aa3b, v26
	v_mul_f32_e32 v21, 0xbfb8aa3b, v30
	v_exp_f32_e32 v20, v20
	v_exp_f32_e32 v21, v21
	v_add_f32_e32 v19, v19, v37
	v_add_f32_e32 v18, v18, v19
	v_add_f32_e32 v19, 1.0, v24
	v_add_f32_e32 v20, 1.0, v20
	v_add_f32_e32 v21, 1.0, v21
	v_mul_f32_e32 v24, 0xbfb8aa3b, v27
	v_rcp_f32_e32 v19, v19
	v_rcp_f32_e32 v20, v20
	v_rcp_f32_e32 v21, v21
	v_exp_f32_e32 v24, v24
	v_mul_f32_e32 v25, v41, v19
	v_mul_f32_e32 v26, v26, v20
	v_mul_f32_e32 v28, v30, v21
	v_add_f32_e32 v19, 1.0, v24
	v_mul_f32_e32 v20, 0xbfb8aa3b, v31
	v_mul_f32_e32 v21, 0xbfb8aa3b, v22
	v_rcp_f32_e32 v19, v19
	v_exp_f32_e32 v20, v20
	v_exp_f32_e32 v21, v21
	v_mul_f32_e32 v24, v27, v19
	v_add_f32_e32 v19, 1.0, v20
	v_add_f32_e32 v20, 1.0, v21
	v_mul_f32_e32 v21, 0xbfb8aa3b, v23
	v_mul_f32_e32 v27, 0xbfb8aa3b, v18
	v_exp_f32_e32 v21, v21
	v_exp_f32_e32 v27, v27
	v_rcp_f32_e32 v19, v19
	v_rcp_f32_e32 v20, v20
	v_add_f32_e32 v21, 1.0, v21
	v_add_f32_e32 v27, 1.0, v27
	v_rcp_f32_e32 v21, v21
	v_rcp_f32_e32 v27, v27
	v_mul_f32_e32 v29, v31, v19
	v_mul_f32_e32 v22, v22, v20
	v_mul_f32_e32 v23, v23, v21
	v_mul_f32_e32 v27, v18, v27
	v_cvt_pk_bf16_f32 v18, v25, v26
	v_cvt_pk_bf16_f32 v19, v28, v24
	v_cvt_pk_bf16_f32 v20, v29, v22
	v_cvt_pk_bf16_f32 v21, v23, v27
	ds_write_b128 v229, v[18:21] offset:9216
	ds_read2st64_b32 v[18:19], v107 offset0:1 offset1:3
	s_waitcnt lgkmcnt(0)
	v_sub_f32_e32 v18, v106, v18
	v_exp_f32_e32 v18, v18
	s_nop 0
	v_mul_f32_e32 v18, v19, v18
	v_mul_f32_e32 v19, v25, v18
	v_mul_f32_e32 v20, v26, v18
	v_mul_f32_e32 v21, v28, v18
	v_mul_f32_e32 v22, v22, v18
	v_mul_f32_e32 v23, v23, v18
	v_mul_f32_e32 v24, v24, v18
	v_mul_f32_e32 v25, v29, v18
	v_mul_f32_e32 v26, v27, v18
	v_cvt_pk_bf16_f32 v18, v19, v20
	v_cvt_pk_bf16_f32 v19, v21, v24
	v_cvt_pk_bf16_f32 v20, v25, v22
	v_cvt_pk_bf16_f32 v21, v23, v26
	v_lshl_add_u64 v[22:23], v[152:153], 0, s[64:65]
	global_load_dwordx2 v[184:185], v[22:23], off
	global_load_dwordx2 v[182:183], v[22:23], off offset:16
	global_load_dwordx2 v[180:181], v[22:23], off offset:32
	global_load_dwordx2 v[178:179], v[22:23], off offset:48
	ds_write_b128 v229, v[18:21] offset:27648
	s_waitcnt vmcnt(11)
	ds_write_b128 v224, v[66:69] offset:36864
	v_add_u32_e32 v18, 0x11800, v224
	s_waitcnt vmcnt(10)
	ds_write_b128 v18, v[70:73]
	s_waitcnt vmcnt(9)
	ds_write_b128 v224, v[74:77] offset:45568
	s_waitcnt vmcnt(8)
	ds_write_b128 v18, v[78:81] offset:8704
	s_waitcnt vmcnt(7)
	ds_write_b128 v224, v[82:85] offset:54272
	s_waitcnt vmcnt(6)
	ds_write_b128 v18, v[86:89] offset:17408
	s_waitcnt vmcnt(5)
	ds_write_b128 v224, v[90:93] offset:62976
	s_waitcnt vmcnt(4)
	ds_write_b128 v18, v[94:97] offset:26112
	s_cbranch_scc1 .LBB0_1304
	s_add_i32 s26, s92, 0x80
	s_mul_i32 s30, s26, 0x1800
	s_mul_hi_u32 s27, s26, 0x1800
	s_add_u32 s28, s84, s30
	s_addc_u32 s29, s85, s27
	v_lshl_add_u64 v[20:21], s[28:29], 0, v[138:139]
	global_load_dwordx4 v[50:53], v[20:21], off
	v_lshl_add_u64 v[18:19], s[28:29], 0, v[142:143]
	s_and_saveexec_b64 s[28:29], s[8:9]
	s_cbranch_execz .LBB0_1300
	v_lshl_add_u64 v[22:23], v[18:19], 0, v[158:159]
	global_load_dwordx4 v[58:61], v[22:23], off
